# up K-loop LDS-DMA pieces in SGPR-base + VGPR-offset form: 16 per-iteration 64-bit VALU address adds replaced by SALU
# speedup vs baseline: 1.0000x; 1.0000x over previous
.LBB0_159:
	s_and_b32 s67, s44, 3
	v_and_b32_e32 v17, 48, v16
	v_lshlrev_b32_e32 v18, 6, v16
	s_movk_i32 s44, 0x3c0
	s_add_i32 m0, s9, 0x18000
	v_lshl_add_u64 v[8:9], v[8:9], 0, s[86:87]
	s_lshl_b32 s70, s59, 6
	v_and_or_b32 v17, v18, s44, v17
	s_lshl_b32 s44, s59, 13
	s_lshl_b32 s59, s67, 12
	s_waitcnt vmcnt(2)
	s_barrier
	global_load_lds_dwordx4 v[8:9], off
	v_lshl_add_u64 v[6:7], v[6:7], 0, s[86:87]
	s_add_i32 m0, s9, 0x1a000
	s_add_i32 s71, s9, 0x8000
	s_add_i32 s74, s9, 0xa000
	global_load_lds_dwordx4 v[6:7], off
	v_lshl_add_u64 v[4:5], v[4:5], 0, s[86:87]
	s_mov_b32 m0, s71
	s_add_u32 s76, s6, 0x40080
	global_load_lds_dwordx4 v[4:5], off
	v_lshl_add_u64 v[2:3], v[2:3], 0, s[86:87]
	s_mov_b32 m0, s74
	s_addc_u32 s77, s7, 0
	global_load_lds_dwordx4 v[2:3], off
	s_add_i32 m0, s9, 0x1c000
	v_lshl_add_u64 v[2:3], s[76:77], 0, v[0:1]
	global_load_lds_dwordx4 v[2:3], off
	v_lshl_add_u64 v[2:3], s[76:77], 0, v[134:135]
	s_add_i32 m0, s9, 0x1e000
	v_lshlrev_b32_e32 v16, 2, v16
	global_load_lds_dwordx4 v[2:3], off
	s_waitcnt vmcnt(6)
	s_barrier
	s_load_dwordx2 s[76:77], s[0:1], 0xc8
	v_lshlrev_b32_e32 v2, 14, v10
	v_and_b32_e32 v2, 0xffff8000, v2
	v_and_b32_e32 v16, 32, v16
	v_lshl_add_u32 v2, v11, 11, v2
	s_waitcnt lgkmcnt(0)
	s_add_u32 s76, s76, s58
	s_addc_u32 s77, s77, s45
	v_and_b32_e32 v3, 1, v10
	v_bitop3_b32 v18, v17, s44, v16 bitop3:0xde
	v_lshl_or_b32 v2, v3, 6, v2
	s_add_u32 s44, s33, s58
	v_lshl_add_u32 v2, v12, 1, v2
	v_mov_b32_e32 v3, v1
	s_addc_u32 s45, s42, s45
	v_add_u32_e32 v136, 0, v2
	v_lshlrev_b32_e32 v2, 14, v13
	v_and_b32_e32 v2, 0xffff8000, v2
	v_lshl_add_u32 v2, v14, 11, v2
	v_and_b32_e32 v3, 1, v13
	v_lshl_or_b32 v2, v3, 6, v2
	v_lshl_add_u32 v2, v15, 1, v2
	v_mov_b32_e32 v3, v1
	v_add_u32_e32 v138, 0, v2
	s_add_u32 s78, s43, s38
	v_bitop3_b32 v140, v17, s59, v16 bitop3:0xde
	s_addc_u32 s79, s46, s39
	s_mov_b32 s81, -2
	s_mov_b64 s[38:39], 0
	v_add_u32_e32 v141, 0, v18
	s_add_u32 s44, s76, s38
	s_addc_u32 s45, s77, s39
	s_add_u32 s44, s44, 0x3800900
	s_addc_u32 s45, s45, 0
	s_add_u32 s100, s44, 0x3ff80
	s_addc_u32 s101, s45, 0
	s_add_u32 s85, s78, s38
	s_addc_u32 s93, s79, s39
	s_add_i32 vcc_lo, 0, 0x10000
	s_cmpk_eq_i32 s38, 0x700
	s_cselect_b32 s59, s29, s45
	s_cselect_b32 s58, s28, s44
	s_cselect_b32 s45, s7, s93
	s_cselect_b32 s44, s6, s85
	s_add_i32 s85, 0, 0x14000
	v_add_u32_e32 v154, vcc_lo, v140
	v_add_u32_e32 v170, s85, v140
	ds_read_b128 v[142:145], v154
	ds_read_b128 v[146:149], v154 offset:1024
	ds_read_b128 v[150:153], v154 offset:2048
	ds_read_b128 v[154:157], v154 offset:3072
	ds_read_b128 v[158:161], v170
	ds_read_b128 v[162:165], v170 offset:1024
	ds_read_b128 v[166:169], v170 offset:2048
	ds_read_b128 v[170:173], v170 offset:3072
	s_add_i32 m0, s9, 0xc000
	ds_read_b128 v[174:177], v141
	ds_read_b128 v[178:181], v141 offset:1024
	ds_read_b128 v[182:185], v141 offset:2048
	ds_read_b128 v[186:189], v141 offset:3072
	ds_read_b128 v[192:195], v141 offset:4096
	ds_read_b128 v[196:199], v141 offset:5120
	ds_read_b128 v[200:203], v141 offset:6144
	ds_read_b128 v[204:207], v141 offset:7168
	global_load_lds_dwordx4 v136, s[100:101]
	s_add_i32 m0, s9, 0xe000
	s_nop 0
	global_load_lds_dwordx4 v138, s[100:101]
	s_waitcnt vmcnt(8)
	s_waitcnt lgkmcnt(0)
	s_barrier
	s_setprio 1
	s_waitcnt lgkmcnt(0)
	v_mfma_f32_16x16x32_bf16 v[126:129], v[142:145], v[174:177], 0
	v_mfma_f32_16x16x32_bf16 v[122:125], v[150:153], v[174:177], 0
	v_mfma_f32_16x16x32_bf16 v[118:121], v[142:145], v[182:185], 0
	v_mfma_f32_16x16x32_bf16 v[114:117], v[150:153], v[182:185], 0
	v_mfma_f32_16x16x32_bf16 v[102:105], v[142:145], v[192:195], 0
	v_mfma_f32_16x16x32_bf16 v[98:101], v[150:153], v[192:195], 0
	v_mfma_f32_16x16x32_bf16 v[86:89], v[142:145], v[200:203], 0
	v_mfma_f32_16x16x32_bf16 v[82:85], v[150:153], v[200:203], 0
	v_mfma_f32_16x16x32_bf16 v[126:129], v[146:149], v[178:181], v[126:129]
	v_mfma_f32_16x16x32_bf16 v[122:125], v[154:157], v[178:181], v[122:125]
	v_mfma_f32_16x16x32_bf16 v[118:121], v[146:149], v[186:189], v[118:121]
	v_mfma_f32_16x16x32_bf16 v[114:117], v[154:157], v[186:189], v[114:117]
	v_mfma_f32_16x16x32_bf16 v[102:105], v[146:149], v[196:199], v[102:105]
	v_mfma_f32_16x16x32_bf16 v[98:101], v[154:157], v[196:199], v[98:101]
	v_mfma_f32_16x16x32_bf16 v[86:89], v[146:149], v[204:207], v[86:89]
	v_mfma_f32_16x16x32_bf16 v[82:85], v[154:157], v[204:207], v[82:85]
	s_setprio 0
	s_setprio 1
	v_mfma_f32_16x16x32_bf16 v[110:113], v[158:161], v[174:177], 0
	v_mfma_f32_16x16x32_bf16 v[106:109], v[166:169], v[174:177], 0
	v_mfma_f32_16x16x32_bf16 v[94:97], v[158:161], v[182:185], 0
	v_mfma_f32_16x16x32_bf16 v[90:93], v[166:169], v[182:185], 0
	v_mfma_f32_16x16x32_bf16 v[78:81], v[158:161], v[192:195], 0
	v_mfma_f32_16x16x32_bf16 v[74:77], v[166:169], v[192:195], 0
	v_mfma_f32_16x16x32_bf16 v[70:73], v[158:161], v[200:203], 0
	v_mfma_f32_16x16x32_bf16 v[66:69], v[166:169], v[200:203], 0
	v_mfma_f32_16x16x32_bf16 v[110:113], v[162:165], v[178:181], v[110:113]
	v_mfma_f32_16x16x32_bf16 v[106:109], v[170:173], v[178:181], v[106:109]
	v_mfma_f32_16x16x32_bf16 v[94:97], v[162:165], v[186:189], v[94:97]
	v_mfma_f32_16x16x32_bf16 v[90:93], v[170:173], v[186:189], v[90:93]
	v_mfma_f32_16x16x32_bf16 v[78:81], v[162:165], v[196:199], v[78:81]
	v_mfma_f32_16x16x32_bf16 v[74:77], v[170:173], v[196:199], v[74:77]
	v_mfma_f32_16x16x32_bf16 v[70:73], v[162:165], v[204:207], v[70:73]
	v_mfma_f32_16x16x32_bf16 v[66:69], v[170:173], v[204:207], v[66:69]
	s_setprio 0
	s_barrier
	s_add_i32 s93, vcc_lo, s49
	s_mov_b32 m0, s93
	ds_read_b128 v[174:177], v141 offset:16384
	ds_read_b128 v[178:181], v141 offset:17408
	ds_read_b128 v[182:185], v141 offset:18432
	ds_read_b128 v[186:189], v141 offset:19456
	ds_read_b128 v[192:195], v141 offset:20480
	ds_read_b128 v[196:199], v141 offset:21504
	ds_read_b128 v[200:203], v141 offset:22528
	ds_read_b128 v[204:207], v141 offset:23552
	global_load_lds_dwordx4 v0, s[44:45]
	s_add_i32 m0, s93, 0x2000
	s_add_u32 s100, s44, 0x40000
	s_addc_u32 s101, s45, 0
	s_add_i32 s85, s85, s49
	global_load_lds_dwordx4 v134, s[44:45]
	s_mov_b32 m0, s85
	s_nop 0
	global_load_lds_dwordx4 v0, s[100:101]
	s_add_i32 m0, s85, 0x2000
	s_nop 0
	global_load_lds_dwordx4 v134, s[100:101]
	s_mov_b32 m0, s9
	s_nop 0
	global_load_lds_dwordx4 v130, s[58:59]
	s_mov_b32 m0, s56
	s_nop 0
	global_load_lds_dwordx4 v132, s[58:59]
	s_waitcnt vmcnt(8)
	s_waitcnt lgkmcnt(0)
	s_barrier
	s_setprio 1
	s_waitcnt lgkmcnt(0)
	v_mfma_f32_16x16x32_bf16 v[62:65], v[142:145], v[174:177], 0
	v_mfma_f32_16x16x32_bf16 v[58:61], v[150:153], v[174:177], 0
	v_mfma_f32_16x16x32_bf16 v[54:57], v[142:145], v[182:185], 0
	v_mfma_f32_16x16x32_bf16 v[50:53], v[150:153], v[182:185], 0
	v_mfma_f32_16x16x32_bf16 v[38:41], v[142:145], v[192:195], 0
	v_mfma_f32_16x16x32_bf16 v[34:37], v[150:153], v[192:195], 0
	v_mfma_f32_16x16x32_bf16 v[22:25], v[142:145], v[200:203], 0
	v_mfma_f32_16x16x32_bf16 v[18:21], v[150:153], v[200:203], 0
	v_mfma_f32_16x16x32_bf16 v[62:65], v[146:149], v[178:181], v[62:65]
	v_mfma_f32_16x16x32_bf16 v[58:61], v[154:157], v[178:181], v[58:61]
	v_mfma_f32_16x16x32_bf16 v[54:57], v[146:149], v[186:189], v[54:57]
	v_mfma_f32_16x16x32_bf16 v[50:53], v[154:157], v[186:189], v[50:53]
	v_mfma_f32_16x16x32_bf16 v[38:41], v[146:149], v[196:199], v[38:41]
	v_mfma_f32_16x16x32_bf16 v[34:37], v[154:157], v[196:199], v[34:37]
	v_mfma_f32_16x16x32_bf16 v[22:25], v[146:149], v[204:207], v[22:25]
	v_mfma_f32_16x16x32_bf16 v[18:21], v[154:157], v[204:207], v[18:21]
	s_setprio 0
	s_setprio 1
	v_mfma_f32_16x16x32_bf16 v[46:49], v[158:161], v[174:177], 0
	v_mfma_f32_16x16x32_bf16 v[42:45], v[166:169], v[174:177], 0
	v_mfma_f32_16x16x32_bf16 v[30:33], v[158:161], v[182:185], 0
	v_mfma_f32_16x16x32_bf16 v[26:29], v[166:169], v[182:185], 0
	v_mfma_f32_16x16x32_bf16 v[14:17], v[158:161], v[192:195], 0
	v_mfma_f32_16x16x32_bf16 v[10:13], v[166:169], v[192:195], 0
	v_mfma_f32_16x16x32_bf16 v[6:9], v[158:161], v[200:203], 0
	v_mfma_f32_16x16x32_bf16 v[2:5], v[166:169], v[200:203], 0
	v_mfma_f32_16x16x32_bf16 v[46:49], v[162:165], v[178:181], v[46:49]
	v_mfma_f32_16x16x32_bf16 v[42:45], v[170:173], v[178:181], v[42:45]
	v_mfma_f32_16x16x32_bf16 v[30:33], v[162:165], v[186:189], v[30:33]
	v_mfma_f32_16x16x32_bf16 v[26:29], v[170:173], v[186:189], v[26:29]
	v_mfma_f32_16x16x32_bf16 v[14:17], v[162:165], v[196:199], v[14:17]
	v_mfma_f32_16x16x32_bf16 v[10:13], v[170:173], v[196:199], v[10:13]
	v_mfma_f32_16x16x32_bf16 v[6:9], v[162:165], v[204:207], v[6:9]
	v_mfma_f32_16x16x32_bf16 v[2:5], v[170:173], v[204:207], v[2:5]
	s_setprio 0
	s_barrier
	s_add_i32 s85, 0, 0x18000
	s_add_i32 s93, 0, 0x1c000
	v_add_u32_e32 v154, s85, v140
	v_add_u32_e32 v170, s93, v140
	ds_read_b128 v[142:145], v154
	ds_read_b128 v[146:149], v154 offset:1024
	ds_read_b128 v[150:153], v154 offset:2048
	ds_read_b128 v[154:157], v154 offset:3072
	ds_read_b128 v[158:161], v170
	ds_read_b128 v[162:165], v170 offset:1024
	ds_read_b128 v[166:169], v170 offset:2048
	ds_read_b128 v[170:173], v170 offset:3072
	s_add_u32 s58, s58, 0x40000
	s_addc_u32 s59, s59, 0
	s_mov_b32 m0, s57
	ds_read_b128 v[174:177], v141 offset:32768
	ds_read_b128 v[178:181], v141 offset:33792
	ds_read_b128 v[182:185], v141 offset:34816
	ds_read_b128 v[186:189], v141 offset:35840
	ds_read_b128 v[192:195], v141 offset:36864
	ds_read_b128 v[196:199], v141 offset:37888
	ds_read_b128 v[200:203], v141 offset:38912
	ds_read_b128 v[204:207], v141 offset:39936
	global_load_lds_dwordx4 v130, s[58:59]
	s_mov_b32 m0, s66
	s_nop 0
	global_load_lds_dwordx4 v132, s[58:59]
	s_waitcnt vmcnt(8)
	s_waitcnt lgkmcnt(0)
	s_barrier
	s_setprio 1
	s_waitcnt lgkmcnt(0)
	v_mfma_f32_16x16x32_bf16 v[126:129], v[142:145], v[174:177], v[126:129]
	v_mfma_f32_16x16x32_bf16 v[122:125], v[150:153], v[174:177], v[122:125]
	v_mfma_f32_16x16x32_bf16 v[118:121], v[142:145], v[182:185], v[118:121]
	v_mfma_f32_16x16x32_bf16 v[114:117], v[150:153], v[182:185], v[114:117]
	v_mfma_f32_16x16x32_bf16 v[102:105], v[142:145], v[192:195], v[102:105]
	v_mfma_f32_16x16x32_bf16 v[98:101], v[150:153], v[192:195], v[98:101]
	v_mfma_f32_16x16x32_bf16 v[86:89], v[142:145], v[200:203], v[86:89]
	v_mfma_f32_16x16x32_bf16 v[82:85], v[150:153], v[200:203], v[82:85]
	v_mfma_f32_16x16x32_bf16 v[126:129], v[146:149], v[178:181], v[126:129]
	v_mfma_f32_16x16x32_bf16 v[122:125], v[154:157], v[178:181], v[122:125]
	v_mfma_f32_16x16x32_bf16 v[118:121], v[146:149], v[186:189], v[118:121]
	v_mfma_f32_16x16x32_bf16 v[114:117], v[154:157], v[186:189], v[114:117]
	v_mfma_f32_16x16x32_bf16 v[102:105], v[146:149], v[196:199], v[102:105]
	v_mfma_f32_16x16x32_bf16 v[98:101], v[154:157], v[196:199], v[98:101]
	v_mfma_f32_16x16x32_bf16 v[86:89], v[146:149], v[204:207], v[86:89]
	v_mfma_f32_16x16x32_bf16 v[82:85], v[154:157], v[204:207], v[82:85]
	s_setprio 0
	s_setprio 1
	v_mfma_f32_16x16x32_bf16 v[110:113], v[158:161], v[174:177], v[110:113]
	v_mfma_f32_16x16x32_bf16 v[106:109], v[166:169], v[174:177], v[106:109]
	v_mfma_f32_16x16x32_bf16 v[94:97], v[158:161], v[182:185], v[94:97]
	v_mfma_f32_16x16x32_bf16 v[90:93], v[166:169], v[182:185], v[90:93]
	v_mfma_f32_16x16x32_bf16 v[78:81], v[158:161], v[192:195], v[78:81]
	v_mfma_f32_16x16x32_bf16 v[74:77], v[166:169], v[192:195], v[74:77]
	v_mfma_f32_16x16x32_bf16 v[70:73], v[158:161], v[200:203], v[70:73]
	v_mfma_f32_16x16x32_bf16 v[66:69], v[166:169], v[200:203], v[66:69]
	v_mfma_f32_16x16x32_bf16 v[110:113], v[162:165], v[178:181], v[110:113]
	v_mfma_f32_16x16x32_bf16 v[106:109], v[170:173], v[178:181], v[106:109]
	v_mfma_f32_16x16x32_bf16 v[94:97], v[162:165], v[186:189], v[94:97]
	v_mfma_f32_16x16x32_bf16 v[90:93], v[170:173], v[186:189], v[90:93]
	v_mfma_f32_16x16x32_bf16 v[78:81], v[162:165], v[196:199], v[78:81]
	v_mfma_f32_16x16x32_bf16 v[74:77], v[170:173], v[196:199], v[74:77]
	v_mfma_f32_16x16x32_bf16 v[70:73], v[162:165], v[204:207], v[70:73]
	v_mfma_f32_16x16x32_bf16 v[66:69], v[170:173], v[204:207], v[66:69]
	s_setprio 0
	s_barrier
	s_add_i32 m0, s85, s49
	s_add_u32 s100, s44, 0x80
	s_addc_u32 s101, s45, 0
	ds_read_b128 v[174:177], v141 offset:49152
	ds_read_b128 v[178:181], v141 offset:50176
	ds_read_b128 v[182:185], v141 offset:51200
	ds_read_b128 v[186:189], v141 offset:52224
	ds_read_b128 v[192:195], v141 offset:53248
	ds_read_b128 v[196:199], v141 offset:54272
	ds_read_b128 v[200:203], v141 offset:55296
	ds_read_b128 v[204:207], v141 offset:56320
	global_load_lds_dwordx4 v0, s[100:101]
	s_add_i32 m0, m0, 0x2000
	s_add_u32 s44, s44, 0x40080
	s_addc_u32 s45, s45, 0
	s_add_i32 s85, s93, s49
	global_load_lds_dwordx4 v134, s[100:101]
	s_mov_b32 m0, s85
	s_nop 0
	global_load_lds_dwordx4 v0, s[44:45]
	s_add_i32 m0, s85, 0x2000
	s_sub_u32 s100, s58, 0x3ff80
	s_subb_u32 s101, s59, 0
	global_load_lds_dwordx4 v134, s[44:45]
	s_mov_b32 m0, s71
	s_nop 0
	global_load_lds_dwordx4 v130, s[100:101]
	s_mov_b32 m0, s74
	s_nop 0
	global_load_lds_dwordx4 v132, s[100:101]
	s_waitcnt vmcnt(8)
	s_waitcnt lgkmcnt(0)
	s_barrier
	s_setprio 1
	s_waitcnt lgkmcnt(0)
	v_mfma_f32_16x16x32_bf16 v[62:65], v[142:145], v[174:177], v[62:65]
	v_mfma_f32_16x16x32_bf16 v[58:61], v[150:153], v[174:177], v[58:61]
	v_mfma_f32_16x16x32_bf16 v[54:57], v[142:145], v[182:185], v[54:57]
	v_mfma_f32_16x16x32_bf16 v[50:53], v[150:153], v[182:185], v[50:53]
	v_mfma_f32_16x16x32_bf16 v[38:41], v[142:145], v[192:195], v[38:41]
	v_mfma_f32_16x16x32_bf16 v[34:37], v[150:153], v[192:195], v[34:37]
	v_mfma_f32_16x16x32_bf16 v[22:25], v[142:145], v[200:203], v[22:25]
	v_mfma_f32_16x16x32_bf16 v[18:21], v[150:153], v[200:203], v[18:21]
	v_mfma_f32_16x16x32_bf16 v[62:65], v[146:149], v[178:181], v[62:65]
	v_mfma_f32_16x16x32_bf16 v[58:61], v[154:157], v[178:181], v[58:61]
	v_mfma_f32_16x16x32_bf16 v[54:57], v[146:149], v[186:189], v[54:57]
	v_mfma_f32_16x16x32_bf16 v[50:53], v[154:157], v[186:189], v[50:53]
	v_mfma_f32_16x16x32_bf16 v[38:41], v[146:149], v[196:199], v[38:41]
	v_mfma_f32_16x16x32_bf16 v[34:37], v[154:157], v[196:199], v[34:37]
	v_mfma_f32_16x16x32_bf16 v[22:25], v[146:149], v[204:207], v[22:25]
	v_mfma_f32_16x16x32_bf16 v[18:21], v[154:157], v[204:207], v[18:21]
	s_setprio 0
	s_setprio 1
	v_mfma_f32_16x16x32_bf16 v[46:49], v[158:161], v[174:177], v[46:49]
	v_mfma_f32_16x16x32_bf16 v[42:45], v[166:169], v[174:177], v[42:45]
	v_mfma_f32_16x16x32_bf16 v[30:33], v[158:161], v[182:185], v[30:33]
	v_mfma_f32_16x16x32_bf16 v[26:29], v[166:169], v[182:185], v[26:29]
	v_mfma_f32_16x16x32_bf16 v[14:17], v[158:161], v[192:195], v[14:17]
	v_mfma_f32_16x16x32_bf16 v[10:13], v[166:169], v[192:195], v[10:13]
	v_mfma_f32_16x16x32_bf16 v[6:9], v[158:161], v[200:203], v[6:9]
	v_mfma_f32_16x16x32_bf16 v[2:5], v[166:169], v[200:203], v[2:5]
	v_mfma_f32_16x16x32_bf16 v[46:49], v[162:165], v[178:181], v[46:49]
	v_mfma_f32_16x16x32_bf16 v[42:45], v[170:173], v[178:181], v[42:45]
	v_mfma_f32_16x16x32_bf16 v[30:33], v[162:165], v[186:189], v[30:33]
	v_mfma_f32_16x16x32_bf16 v[26:29], v[170:173], v[186:189], v[26:29]
	v_mfma_f32_16x16x32_bf16 v[14:17], v[162:165], v[196:199], v[14:17]
	v_mfma_f32_16x16x32_bf16 v[10:13], v[170:173], v[196:199], v[10:13]
	v_mfma_f32_16x16x32_bf16 v[6:9], v[162:165], v[204:207], v[6:9]
	v_mfma_f32_16x16x32_bf16 v[2:5], v[170:173], v[204:207], v[2:5]
	s_setprio 0
	s_barrier
	s_add_i32 s81, s81, 2
	s_add_u32 s38, s38, 0x100
	s_addc_u32 s39, s39, 0
	s_cmp_lt_u32 s81, 14
.LBB0_160:
	s_add_u32 s44, s76, s38
	s_addc_u32 s45, s77, s39
	s_add_u32 s44, s44, 0x3800900
	s_addc_u32 s45, s45, 0
	s_add_u32 s100, s44, 0x3ff80
	s_addc_u32 s101, s45, 0
	s_add_u32 s85, s78, s38
	s_addc_u32 s93, s79, s39
	s_add_i32 vcc_lo, 0, 0x10000
	s_cmpk_eq_i32 s38, 0x700
	s_cselect_b32 s59, s29, s45
	s_cselect_b32 s58, s28, s44
	s_cselect_b32 s45, s7, s93
	s_cselect_b32 s44, s6, s85
	s_add_i32 s85, 0, 0x14000
	v_add_u32_e32 v154, vcc_lo, v140
	v_add_u32_e32 v170, s85, v140
	ds_read_b128 v[142:145], v154
	ds_read_b128 v[146:149], v154 offset:1024
	ds_read_b128 v[150:153], v154 offset:2048
	ds_read_b128 v[154:157], v154 offset:3072
	ds_read_b128 v[158:161], v170
	ds_read_b128 v[162:165], v170 offset:1024
	ds_read_b128 v[166:169], v170 offset:2048
	ds_read_b128 v[170:173], v170 offset:3072
	s_add_i32 m0, s9, 0xc000
	ds_read_b128 v[174:177], v141
	ds_read_b128 v[178:181], v141 offset:1024
	ds_read_b128 v[182:185], v141 offset:2048
	ds_read_b128 v[186:189], v141 offset:3072
	ds_read_b128 v[192:195], v141 offset:4096
	ds_read_b128 v[196:199], v141 offset:5120
	ds_read_b128 v[200:203], v141 offset:6144
	ds_read_b128 v[204:207], v141 offset:7168
	global_load_lds_dwordx4 v136, s[100:101]
	s_add_i32 m0, s9, 0xe000
	s_nop 0
	global_load_lds_dwordx4 v138, s[100:101]
	s_waitcnt vmcnt(8)
	s_waitcnt lgkmcnt(0)
	s_barrier
	s_setprio 1
	s_waitcnt lgkmcnt(0)
	v_mfma_f32_16x16x32_bf16 v[126:129], v[142:145], v[174:177], v[126:129]
	v_mfma_f32_16x16x32_bf16 v[122:125], v[150:153], v[174:177], v[122:125]
	v_mfma_f32_16x16x32_bf16 v[118:121], v[142:145], v[182:185], v[118:121]
	v_mfma_f32_16x16x32_bf16 v[114:117], v[150:153], v[182:185], v[114:117]
	v_mfma_f32_16x16x32_bf16 v[102:105], v[142:145], v[192:195], v[102:105]
	v_mfma_f32_16x16x32_bf16 v[98:101], v[150:153], v[192:195], v[98:101]
	v_mfma_f32_16x16x32_bf16 v[86:89], v[142:145], v[200:203], v[86:89]
	v_mfma_f32_16x16x32_bf16 v[82:85], v[150:153], v[200:203], v[82:85]
	v_mfma_f32_16x16x32_bf16 v[126:129], v[146:149], v[178:181], v[126:129]
	v_mfma_f32_16x16x32_bf16 v[122:125], v[154:157], v[178:181], v[122:125]
	v_mfma_f32_16x16x32_bf16 v[118:121], v[146:149], v[186:189], v[118:121]
	v_mfma_f32_16x16x32_bf16 v[114:117], v[154:157], v[186:189], v[114:117]
	v_mfma_f32_16x16x32_bf16 v[102:105], v[146:149], v[196:199], v[102:105]
	v_mfma_f32_16x16x32_bf16 v[98:101], v[154:157], v[196:199], v[98:101]
	v_mfma_f32_16x16x32_bf16 v[86:89], v[146:149], v[204:207], v[86:89]
	v_mfma_f32_16x16x32_bf16 v[82:85], v[154:157], v[204:207], v[82:85]
	s_setprio 0
	s_setprio 1
	v_mfma_f32_16x16x32_bf16 v[110:113], v[158:161], v[174:177], v[110:113]
	v_mfma_f32_16x16x32_bf16 v[106:109], v[166:169], v[174:177], v[106:109]
	v_mfma_f32_16x16x32_bf16 v[94:97], v[158:161], v[182:185], v[94:97]
	v_mfma_f32_16x16x32_bf16 v[90:93], v[166:169], v[182:185], v[90:93]
	v_mfma_f32_16x16x32_bf16 v[78:81], v[158:161], v[192:195], v[78:81]
	v_mfma_f32_16x16x32_bf16 v[74:77], v[166:169], v[192:195], v[74:77]
	v_mfma_f32_16x16x32_bf16 v[70:73], v[158:161], v[200:203], v[70:73]
	v_mfma_f32_16x16x32_bf16 v[66:69], v[166:169], v[200:203], v[66:69]
	v_mfma_f32_16x16x32_bf16 v[110:113], v[162:165], v[178:181], v[110:113]
	v_mfma_f32_16x16x32_bf16 v[106:109], v[170:173], v[178:181], v[106:109]
	v_mfma_f32_16x16x32_bf16 v[94:97], v[162:165], v[186:189], v[94:97]
	v_mfma_f32_16x16x32_bf16 v[90:93], v[170:173], v[186:189], v[90:93]
	v_mfma_f32_16x16x32_bf16 v[78:81], v[162:165], v[196:199], v[78:81]
	v_mfma_f32_16x16x32_bf16 v[74:77], v[170:173], v[196:199], v[74:77]
	v_mfma_f32_16x16x32_bf16 v[70:73], v[162:165], v[204:207], v[70:73]
	v_mfma_f32_16x16x32_bf16 v[66:69], v[170:173], v[204:207], v[66:69]
	s_setprio 0
	s_barrier
	s_add_i32 s93, vcc_lo, s49
	s_mov_b32 m0, s93
	ds_read_b128 v[174:177], v141 offset:16384
	ds_read_b128 v[178:181], v141 offset:17408
	ds_read_b128 v[182:185], v141 offset:18432
	ds_read_b128 v[186:189], v141 offset:19456
	ds_read_b128 v[192:195], v141 offset:20480
	ds_read_b128 v[196:199], v141 offset:21504
	ds_read_b128 v[200:203], v141 offset:22528
	ds_read_b128 v[204:207], v141 offset:23552
	global_load_lds_dwordx4 v0, s[44:45]
	s_add_i32 m0, s93, 0x2000
	s_add_u32 s100, s44, 0x40000
	s_addc_u32 s101, s45, 0
	s_add_i32 s85, s85, s49
	global_load_lds_dwordx4 v134, s[44:45]
	s_mov_b32 m0, s85
	s_nop 0
	global_load_lds_dwordx4 v0, s[100:101]
	s_add_i32 m0, s85, 0x2000
	s_nop 0
	global_load_lds_dwordx4 v134, s[100:101]
	s_mov_b32 m0, s9
	s_nop 0
	global_load_lds_dwordx4 v130, s[58:59]
	s_mov_b32 m0, s56
	s_nop 0
	global_load_lds_dwordx4 v132, s[58:59]
	s_waitcnt vmcnt(8)
	s_waitcnt lgkmcnt(0)
	s_barrier
	s_setprio 1
	s_waitcnt lgkmcnt(0)
	v_mfma_f32_16x16x32_bf16 v[62:65], v[142:145], v[174:177], v[62:65]
	v_mfma_f32_16x16x32_bf16 v[58:61], v[150:153], v[174:177], v[58:61]
	v_mfma_f32_16x16x32_bf16 v[54:57], v[142:145], v[182:185], v[54:57]
	v_mfma_f32_16x16x32_bf16 v[50:53], v[150:153], v[182:185], v[50:53]
	v_mfma_f32_16x16x32_bf16 v[38:41], v[142:145], v[192:195], v[38:41]
	v_mfma_f32_16x16x32_bf16 v[34:37], v[150:153], v[192:195], v[34:37]
	v_mfma_f32_16x16x32_bf16 v[22:25], v[142:145], v[200:203], v[22:25]
	v_mfma_f32_16x16x32_bf16 v[18:21], v[150:153], v[200:203], v[18:21]
	v_mfma_f32_16x16x32_bf16 v[62:65], v[146:149], v[178:181], v[62:65]
	v_mfma_f32_16x16x32_bf16 v[58:61], v[154:157], v[178:181], v[58:61]
	v_mfma_f32_16x16x32_bf16 v[54:57], v[146:149], v[186:189], v[54:57]
	v_mfma_f32_16x16x32_bf16 v[50:53], v[154:157], v[186:189], v[50:53]
	v_mfma_f32_16x16x32_bf16 v[38:41], v[146:149], v[196:199], v[38:41]
	v_mfma_f32_16x16x32_bf16 v[34:37], v[154:157], v[196:199], v[34:37]
	v_mfma_f32_16x16x32_bf16 v[22:25], v[146:149], v[204:207], v[22:25]
	v_mfma_f32_16x16x32_bf16 v[18:21], v[154:157], v[204:207], v[18:21]
	s_setprio 0
	s_setprio 1
	v_mfma_f32_16x16x32_bf16 v[46:49], v[158:161], v[174:177], v[46:49]
	v_mfma_f32_16x16x32_bf16 v[42:45], v[166:169], v[174:177], v[42:45]
	v_mfma_f32_16x16x32_bf16 v[30:33], v[158:161], v[182:185], v[30:33]
	v_mfma_f32_16x16x32_bf16 v[26:29], v[166:169], v[182:185], v[26:29]
	v_mfma_f32_16x16x32_bf16 v[14:17], v[158:161], v[192:195], v[14:17]
	v_mfma_f32_16x16x32_bf16 v[10:13], v[166:169], v[192:195], v[10:13]
	v_mfma_f32_16x16x32_bf16 v[6:9], v[158:161], v[200:203], v[6:9]
	v_mfma_f32_16x16x32_bf16 v[2:5], v[166:169], v[200:203], v[2:5]
	v_mfma_f32_16x16x32_bf16 v[46:49], v[162:165], v[178:181], v[46:49]
	v_mfma_f32_16x16x32_bf16 v[42:45], v[170:173], v[178:181], v[42:45]
	v_mfma_f32_16x16x32_bf16 v[30:33], v[162:165], v[186:189], v[30:33]
	v_mfma_f32_16x16x32_bf16 v[26:29], v[170:173], v[186:189], v[26:29]
	v_mfma_f32_16x16x32_bf16 v[14:17], v[162:165], v[196:199], v[14:17]
	v_mfma_f32_16x16x32_bf16 v[10:13], v[170:173], v[196:199], v[10:13]
	v_mfma_f32_16x16x32_bf16 v[6:9], v[162:165], v[204:207], v[6:9]
	v_mfma_f32_16x16x32_bf16 v[2:5], v[170:173], v[204:207], v[2:5]
	s_setprio 0
	s_barrier
	s_add_i32 s85, 0, 0x18000
	s_add_i32 s93, 0, 0x1c000
	v_add_u32_e32 v154, s85, v140
	v_add_u32_e32 v170, s93, v140
	ds_read_b128 v[142:145], v154
	ds_read_b128 v[146:149], v154 offset:1024
	ds_read_b128 v[150:153], v154 offset:2048
	ds_read_b128 v[154:157], v154 offset:3072
	ds_read_b128 v[158:161], v170
	ds_read_b128 v[162:165], v170 offset:1024
	ds_read_b128 v[166:169], v170 offset:2048
	ds_read_b128 v[170:173], v170 offset:3072
	s_add_u32 s58, s58, 0x40000
	s_addc_u32 s59, s59, 0
	s_mov_b32 m0, s57
	ds_read_b128 v[174:177], v141 offset:32768
	ds_read_b128 v[178:181], v141 offset:33792
	ds_read_b128 v[182:185], v141 offset:34816
	ds_read_b128 v[186:189], v141 offset:35840
	ds_read_b128 v[192:195], v141 offset:36864
	ds_read_b128 v[196:199], v141 offset:37888
	ds_read_b128 v[200:203], v141 offset:38912
	ds_read_b128 v[204:207], v141 offset:39936
	global_load_lds_dwordx4 v130, s[58:59]
	s_mov_b32 m0, s66
	s_nop 0
	global_load_lds_dwordx4 v132, s[58:59]
	s_waitcnt vmcnt(8)
	s_waitcnt lgkmcnt(0)
	s_barrier
	s_setprio 1
	s_waitcnt lgkmcnt(0)
	v_mfma_f32_16x16x32_bf16 v[126:129], v[142:145], v[174:177], v[126:129]
	v_mfma_f32_16x16x32_bf16 v[122:125], v[150:153], v[174:177], v[122:125]
	v_mfma_f32_16x16x32_bf16 v[118:121], v[142:145], v[182:185], v[118:121]
	v_mfma_f32_16x16x32_bf16 v[114:117], v[150:153], v[182:185], v[114:117]
	v_mfma_f32_16x16x32_bf16 v[102:105], v[142:145], v[192:195], v[102:105]
	v_mfma_f32_16x16x32_bf16 v[98:101], v[150:153], v[192:195], v[98:101]
	v_mfma_f32_16x16x32_bf16 v[86:89], v[142:145], v[200:203], v[86:89]
	v_mfma_f32_16x16x32_bf16 v[82:85], v[150:153], v[200:203], v[82:85]
	v_mfma_f32_16x16x32_bf16 v[126:129], v[146:149], v[178:181], v[126:129]
	v_mfma_f32_16x16x32_bf16 v[122:125], v[154:157], v[178:181], v[122:125]
	v_mfma_f32_16x16x32_bf16 v[118:121], v[146:149], v[186:189], v[118:121]
	v_mfma_f32_16x16x32_bf16 v[114:117], v[154:157], v[186:189], v[114:117]
	v_mfma_f32_16x16x32_bf16 v[102:105], v[146:149], v[196:199], v[102:105]
	v_mfma_f32_16x16x32_bf16 v[98:101], v[154:157], v[196:199], v[98:101]
	v_mfma_f32_16x16x32_bf16 v[86:89], v[146:149], v[204:207], v[86:89]
	v_mfma_f32_16x16x32_bf16 v[82:85], v[154:157], v[204:207], v[82:85]
	s_setprio 0
	s_setprio 1
	v_mfma_f32_16x16x32_bf16 v[110:113], v[158:161], v[174:177], v[110:113]
	v_mfma_f32_16x16x32_bf16 v[106:109], v[166:169], v[174:177], v[106:109]
	v_mfma_f32_16x16x32_bf16 v[94:97], v[158:161], v[182:185], v[94:97]
	v_mfma_f32_16x16x32_bf16 v[90:93], v[166:169], v[182:185], v[90:93]
	v_mfma_f32_16x16x32_bf16 v[78:81], v[158:161], v[192:195], v[78:81]
	v_mfma_f32_16x16x32_bf16 v[74:77], v[166:169], v[192:195], v[74:77]
	v_mfma_f32_16x16x32_bf16 v[70:73], v[158:161], v[200:203], v[70:73]
	v_mfma_f32_16x16x32_bf16 v[66:69], v[166:169], v[200:203], v[66:69]
	v_mfma_f32_16x16x32_bf16 v[110:113], v[162:165], v[178:181], v[110:113]
	v_mfma_f32_16x16x32_bf16 v[106:109], v[170:173], v[178:181], v[106:109]
	v_mfma_f32_16x16x32_bf16 v[94:97], v[162:165], v[186:189], v[94:97]
	v_mfma_f32_16x16x32_bf16 v[90:93], v[170:173], v[186:189], v[90:93]
	v_mfma_f32_16x16x32_bf16 v[78:81], v[162:165], v[196:199], v[78:81]
	v_mfma_f32_16x16x32_bf16 v[74:77], v[170:173], v[196:199], v[74:77]
	v_mfma_f32_16x16x32_bf16 v[70:73], v[162:165], v[204:207], v[70:73]
	v_mfma_f32_16x16x32_bf16 v[66:69], v[170:173], v[204:207], v[66:69]
	s_setprio 0
	s_barrier
	s_add_i32 m0, s85, s49
	s_add_u32 s100, s44, 0x80
	s_addc_u32 s101, s45, 0
	ds_read_b128 v[174:177], v141 offset:49152
	ds_read_b128 v[178:181], v141 offset:50176
	ds_read_b128 v[182:185], v141 offset:51200
	ds_read_b128 v[186:189], v141 offset:52224
	ds_read_b128 v[192:195], v141 offset:53248
	ds_read_b128 v[196:199], v141 offset:54272
	ds_read_b128 v[200:203], v141 offset:55296
	ds_read_b128 v[204:207], v141 offset:56320
	global_load_lds_dwordx4 v0, s[100:101]
	s_add_i32 m0, m0, 0x2000
	s_add_u32 s44, s44, 0x40080
	s_addc_u32 s45, s45, 0
	s_add_i32 s85, s93, s49
	global_load_lds_dwordx4 v134, s[100:101]
	s_mov_b32 m0, s85
	s_nop 0
	global_load_lds_dwordx4 v0, s[44:45]
	s_add_i32 m0, s85, 0x2000
	s_sub_u32 s100, s58, 0x3ff80
	s_subb_u32 s101, s59, 0
	global_load_lds_dwordx4 v134, s[44:45]
	s_mov_b32 m0, s71
	s_nop 0
	global_load_lds_dwordx4 v130, s[100:101]
	s_mov_b32 m0, s74
	s_nop 0
	global_load_lds_dwordx4 v132, s[100:101]
	s_waitcnt vmcnt(8)
	s_waitcnt lgkmcnt(0)
	s_barrier
	s_setprio 1
	s_waitcnt lgkmcnt(0)
	v_mfma_f32_16x16x32_bf16 v[62:65], v[142:145], v[174:177], v[62:65]
	v_mfma_f32_16x16x32_bf16 v[58:61], v[150:153], v[174:177], v[58:61]
	v_mfma_f32_16x16x32_bf16 v[54:57], v[142:145], v[182:185], v[54:57]
	v_mfma_f32_16x16x32_bf16 v[50:53], v[150:153], v[182:185], v[50:53]
	v_mfma_f32_16x16x32_bf16 v[38:41], v[142:145], v[192:195], v[38:41]
	v_mfma_f32_16x16x32_bf16 v[34:37], v[150:153], v[192:195], v[34:37]
	v_mfma_f32_16x16x32_bf16 v[22:25], v[142:145], v[200:203], v[22:25]
	v_mfma_f32_16x16x32_bf16 v[18:21], v[150:153], v[200:203], v[18:21]
	v_mfma_f32_16x16x32_bf16 v[62:65], v[146:149], v[178:181], v[62:65]
	v_mfma_f32_16x16x32_bf16 v[58:61], v[154:157], v[178:181], v[58:61]
	v_mfma_f32_16x16x32_bf16 v[54:57], v[146:149], v[186:189], v[54:57]
	v_mfma_f32_16x16x32_bf16 v[50:53], v[154:157], v[186:189], v[50:53]
	v_mfma_f32_16x16x32_bf16 v[38:41], v[146:149], v[196:199], v[38:41]
	v_mfma_f32_16x16x32_bf16 v[34:37], v[154:157], v[196:199], v[34:37]
	v_mfma_f32_16x16x32_bf16 v[22:25], v[146:149], v[204:207], v[22:25]
	v_mfma_f32_16x16x32_bf16 v[18:21], v[154:157], v[204:207], v[18:21]
	s_setprio 0
	s_setprio 1
	v_mfma_f32_16x16x32_bf16 v[46:49], v[158:161], v[174:177], v[46:49]
	v_mfma_f32_16x16x32_bf16 v[42:45], v[166:169], v[174:177], v[42:45]
	v_mfma_f32_16x16x32_bf16 v[30:33], v[158:161], v[182:185], v[30:33]
	v_mfma_f32_16x16x32_bf16 v[26:29], v[166:169], v[182:185], v[26:29]
	v_mfma_f32_16x16x32_bf16 v[14:17], v[158:161], v[192:195], v[14:17]
	v_mfma_f32_16x16x32_bf16 v[10:13], v[166:169], v[192:195], v[10:13]
	v_mfma_f32_16x16x32_bf16 v[6:9], v[158:161], v[200:203], v[6:9]
	v_mfma_f32_16x16x32_bf16 v[2:5], v[166:169], v[200:203], v[2:5]
	v_mfma_f32_16x16x32_bf16 v[46:49], v[162:165], v[178:181], v[46:49]
	v_mfma_f32_16x16x32_bf16 v[42:45], v[170:173], v[178:181], v[42:45]
	v_mfma_f32_16x16x32_bf16 v[30:33], v[162:165], v[186:189], v[30:33]
	v_mfma_f32_16x16x32_bf16 v[26:29], v[170:173], v[186:189], v[26:29]
	v_mfma_f32_16x16x32_bf16 v[14:17], v[162:165], v[196:199], v[14:17]
	v_mfma_f32_16x16x32_bf16 v[10:13], v[170:173], v[196:199], v[10:13]
	v_mfma_f32_16x16x32_bf16 v[6:9], v[162:165], v[204:207], v[6:9]
	v_mfma_f32_16x16x32_bf16 v[2:5], v[170:173], v[204:207], v[2:5]
	s_setprio 0
	s_barrier
	s_add_i32 s81, s81, 2
	s_add_u32 s38, s38, 0x100
	s_addc_u32 s39, s39, 0
	s_cmp_lt_u32 s81, 12
	s_cbranch_scc1 .LBB0_160
	s_add_u32 s44, s76, s38
	s_addc_u32 s45, s77, s39
	s_add_u32 s44, s44, 0x3800900
	s_addc_u32 s45, s45, 0
	s_add_u32 s100, s44, 0x3ff80
	s_addc_u32 s101, s45, 0
	s_add_u32 s85, s78, s38
	s_addc_u32 s93, s79, s39
	s_add_i32 vcc_lo, 0, 0x10000
	s_cmpk_eq_i32 s38, 0x700
	s_cselect_b32 s59, s29, s45
	s_cselect_b32 s58, s28, s44
	s_cselect_b32 s45, s7, s93
	s_cselect_b32 s44, s6, s85
	s_add_i32 s85, 0, 0x14000
	v_add_u32_e32 v154, vcc_lo, v140
	v_add_u32_e32 v170, s85, v140
	ds_read_b128 v[142:145], v154
	ds_read_b128 v[146:149], v154 offset:1024
	ds_read_b128 v[150:153], v154 offset:2048
	ds_read_b128 v[154:157], v154 offset:3072
	ds_read_b128 v[158:161], v170
	ds_read_b128 v[162:165], v170 offset:1024
	ds_read_b128 v[166:169], v170 offset:2048
	ds_read_b128 v[170:173], v170 offset:3072
	s_add_i32 m0, s9, 0xc000
	ds_read_b128 v[174:177], v141
	ds_read_b128 v[178:181], v141 offset:1024
	ds_read_b128 v[182:185], v141 offset:2048
	ds_read_b128 v[186:189], v141 offset:3072
	ds_read_b128 v[192:195], v141 offset:4096
	ds_read_b128 v[196:199], v141 offset:5120
	ds_read_b128 v[200:203], v141 offset:6144
	ds_read_b128 v[204:207], v141 offset:7168
	global_load_lds_dwordx4 v136, s[100:101]
	s_add_i32 m0, s9, 0xe000
	s_nop 0
	global_load_lds_dwordx4 v138, s[100:101]
	s_waitcnt vmcnt(8)
	s_waitcnt lgkmcnt(0)
	s_barrier
	s_setprio 1
	s_waitcnt lgkmcnt(0)
	v_mfma_f32_16x16x32_bf16 v[126:129], v[142:145], v[174:177], v[126:129]
	v_mfma_f32_16x16x32_bf16 v[122:125], v[150:153], v[174:177], v[122:125]
	v_mfma_f32_16x16x32_bf16 v[118:121], v[142:145], v[182:185], v[118:121]
	v_mfma_f32_16x16x32_bf16 v[114:117], v[150:153], v[182:185], v[114:117]
	v_mfma_f32_16x16x32_bf16 v[102:105], v[142:145], v[192:195], v[102:105]
	v_mfma_f32_16x16x32_bf16 v[98:101], v[150:153], v[192:195], v[98:101]
	v_mfma_f32_16x16x32_bf16 v[86:89], v[142:145], v[200:203], v[86:89]
	v_mfma_f32_16x16x32_bf16 v[82:85], v[150:153], v[200:203], v[82:85]
	v_mfma_f32_16x16x32_bf16 v[126:129], v[146:149], v[178:181], v[126:129]
	v_mfma_f32_16x16x32_bf16 v[122:125], v[154:157], v[178:181], v[122:125]
	v_mfma_f32_16x16x32_bf16 v[118:121], v[146:149], v[186:189], v[118:121]
	v_mfma_f32_16x16x32_bf16 v[114:117], v[154:157], v[186:189], v[114:117]
	v_mfma_f32_16x16x32_bf16 v[102:105], v[146:149], v[196:199], v[102:105]
	v_mfma_f32_16x16x32_bf16 v[98:101], v[154:157], v[196:199], v[98:101]
	v_mfma_f32_16x16x32_bf16 v[86:89], v[146:149], v[204:207], v[86:89]
	v_mfma_f32_16x16x32_bf16 v[82:85], v[154:157], v[204:207], v[82:85]
	s_setprio 0
	s_setprio 1
	v_mfma_f32_16x16x32_bf16 v[110:113], v[158:161], v[174:177], v[110:113]
	v_mfma_f32_16x16x32_bf16 v[106:109], v[166:169], v[174:177], v[106:109]
	v_mfma_f32_16x16x32_bf16 v[94:97], v[158:161], v[182:185], v[94:97]
	v_mfma_f32_16x16x32_bf16 v[90:93], v[166:169], v[182:185], v[90:93]
	v_mfma_f32_16x16x32_bf16 v[78:81], v[158:161], v[192:195], v[78:81]
	v_mfma_f32_16x16x32_bf16 v[74:77], v[166:169], v[192:195], v[74:77]
	v_mfma_f32_16x16x32_bf16 v[70:73], v[158:161], v[200:203], v[70:73]
	v_mfma_f32_16x16x32_bf16 v[66:69], v[166:169], v[200:203], v[66:69]
	v_mfma_f32_16x16x32_bf16 v[110:113], v[162:165], v[178:181], v[110:113]
	v_mfma_f32_16x16x32_bf16 v[106:109], v[170:173], v[178:181], v[106:109]
	v_mfma_f32_16x16x32_bf16 v[94:97], v[162:165], v[186:189], v[94:97]
	v_mfma_f32_16x16x32_bf16 v[90:93], v[170:173], v[186:189], v[90:93]
	v_mfma_f32_16x16x32_bf16 v[78:81], v[162:165], v[196:199], v[78:81]
	v_mfma_f32_16x16x32_bf16 v[74:77], v[170:173], v[196:199], v[74:77]
	v_mfma_f32_16x16x32_bf16 v[70:73], v[162:165], v[204:207], v[70:73]
	v_mfma_f32_16x16x32_bf16 v[66:69], v[170:173], v[204:207], v[66:69]
	s_setprio 0
	s_barrier
	s_add_i32 s93, vcc_lo, s49
	s_mov_b32 m0, s93
	ds_read_b128 v[174:177], v141 offset:16384
	ds_read_b128 v[178:181], v141 offset:17408
	ds_read_b128 v[182:185], v141 offset:18432
	ds_read_b128 v[186:189], v141 offset:19456
	ds_read_b128 v[192:195], v141 offset:20480
	ds_read_b128 v[196:199], v141 offset:21504
	ds_read_b128 v[200:203], v141 offset:22528
	ds_read_b128 v[204:207], v141 offset:23552
	s_add_i32 m0, s93, 0x2000
	s_add_u32 s100, s44, 0x40000
	s_addc_u32 s101, s45, 0
	s_add_i32 s85, s85, s49
	s_mov_b32 m0, s85
	s_nop 0
	s_add_i32 m0, s85, 0x2000
	s_nop 0
	s_mov_b32 m0, s9
	s_nop 0
	s_mov_b32 m0, s56
	s_nop 0
	s_waitcnt vmcnt(2)
	s_waitcnt lgkmcnt(0)
	s_barrier
	s_setprio 1
	s_waitcnt lgkmcnt(0)
	v_mfma_f32_16x16x32_bf16 v[62:65], v[142:145], v[174:177], v[62:65]
	v_mfma_f32_16x16x32_bf16 v[58:61], v[150:153], v[174:177], v[58:61]
	v_mfma_f32_16x16x32_bf16 v[54:57], v[142:145], v[182:185], v[54:57]
	v_mfma_f32_16x16x32_bf16 v[50:53], v[150:153], v[182:185], v[50:53]
	v_mfma_f32_16x16x32_bf16 v[38:41], v[142:145], v[192:195], v[38:41]
	v_mfma_f32_16x16x32_bf16 v[34:37], v[150:153], v[192:195], v[34:37]
	v_mfma_f32_16x16x32_bf16 v[22:25], v[142:145], v[200:203], v[22:25]
	v_mfma_f32_16x16x32_bf16 v[18:21], v[150:153], v[200:203], v[18:21]
	v_mfma_f32_16x16x32_bf16 v[62:65], v[146:149], v[178:181], v[62:65]
	v_mfma_f32_16x16x32_bf16 v[58:61], v[154:157], v[178:181], v[58:61]
	v_mfma_f32_16x16x32_bf16 v[54:57], v[146:149], v[186:189], v[54:57]
	v_mfma_f32_16x16x32_bf16 v[50:53], v[154:157], v[186:189], v[50:53]
	v_mfma_f32_16x16x32_bf16 v[38:41], v[146:149], v[196:199], v[38:41]
	v_mfma_f32_16x16x32_bf16 v[34:37], v[154:157], v[196:199], v[34:37]
	v_mfma_f32_16x16x32_bf16 v[22:25], v[146:149], v[204:207], v[22:25]
	v_mfma_f32_16x16x32_bf16 v[18:21], v[154:157], v[204:207], v[18:21]
	s_setprio 0
	s_setprio 1
	v_mfma_f32_16x16x32_bf16 v[46:49], v[158:161], v[174:177], v[46:49]
	v_mfma_f32_16x16x32_bf16 v[42:45], v[166:169], v[174:177], v[42:45]
	v_mfma_f32_16x16x32_bf16 v[30:33], v[158:161], v[182:185], v[30:33]
	v_mfma_f32_16x16x32_bf16 v[26:29], v[166:169], v[182:185], v[26:29]
	v_mfma_f32_16x16x32_bf16 v[14:17], v[158:161], v[192:195], v[14:17]
	v_mfma_f32_16x16x32_bf16 v[10:13], v[166:169], v[192:195], v[10:13]
	v_mfma_f32_16x16x32_bf16 v[6:9], v[158:161], v[200:203], v[6:9]
	v_mfma_f32_16x16x32_bf16 v[2:5], v[166:169], v[200:203], v[2:5]
	v_mfma_f32_16x16x32_bf16 v[46:49], v[162:165], v[178:181], v[46:49]
	v_mfma_f32_16x16x32_bf16 v[42:45], v[170:173], v[178:181], v[42:45]
	v_mfma_f32_16x16x32_bf16 v[30:33], v[162:165], v[186:189], v[30:33]
	v_mfma_f32_16x16x32_bf16 v[26:29], v[170:173], v[186:189], v[26:29]
	v_mfma_f32_16x16x32_bf16 v[14:17], v[162:165], v[196:199], v[14:17]
	v_mfma_f32_16x16x32_bf16 v[10:13], v[170:173], v[196:199], v[10:13]
	v_mfma_f32_16x16x32_bf16 v[6:9], v[162:165], v[204:207], v[6:9]
	v_mfma_f32_16x16x32_bf16 v[2:5], v[170:173], v[204:207], v[2:5]
	s_setprio 0
	s_barrier
	s_add_i32 s85, 0, 0x18000
	s_add_i32 s93, 0, 0x1c000
	v_add_u32_e32 v154, s85, v140
	v_add_u32_e32 v170, s93, v140
	ds_read_b128 v[142:145], v154
	ds_read_b128 v[146:149], v154 offset:1024
	ds_read_b128 v[150:153], v154 offset:2048
	ds_read_b128 v[154:157], v154 offset:3072
	ds_read_b128 v[158:161], v170
	ds_read_b128 v[162:165], v170 offset:1024
	ds_read_b128 v[166:169], v170 offset:2048
	ds_read_b128 v[170:173], v170 offset:3072
	s_add_u32 s58, s58, 0x40000
	s_addc_u32 s59, s59, 0
	s_mov_b32 m0, s57
	ds_read_b128 v[174:177], v141 offset:32768
	ds_read_b128 v[178:181], v141 offset:33792
	ds_read_b128 v[182:185], v141 offset:34816
	ds_read_b128 v[186:189], v141 offset:35840
	ds_read_b128 v[192:195], v141 offset:36864
	ds_read_b128 v[196:199], v141 offset:37888
	ds_read_b128 v[200:203], v141 offset:38912
	ds_read_b128 v[204:207], v141 offset:39936
	s_mov_b32 m0, s66
	s_nop 0
	s_waitcnt vmcnt(0)
	s_waitcnt lgkmcnt(0)
	s_barrier
	s_setprio 1
	s_waitcnt lgkmcnt(0)
	v_mfma_f32_16x16x32_bf16 v[126:129], v[142:145], v[174:177], v[126:129]
	v_mfma_f32_16x16x32_bf16 v[122:125], v[150:153], v[174:177], v[122:125]
	v_mfma_f32_16x16x32_bf16 v[118:121], v[142:145], v[182:185], v[118:121]
	v_mfma_f32_16x16x32_bf16 v[114:117], v[150:153], v[182:185], v[114:117]
	v_mfma_f32_16x16x32_bf16 v[102:105], v[142:145], v[192:195], v[102:105]
	v_mfma_f32_16x16x32_bf16 v[98:101], v[150:153], v[192:195], v[98:101]
	v_mfma_f32_16x16x32_bf16 v[86:89], v[142:145], v[200:203], v[86:89]
	v_mfma_f32_16x16x32_bf16 v[82:85], v[150:153], v[200:203], v[82:85]
	v_mfma_f32_16x16x32_bf16 v[126:129], v[146:149], v[178:181], v[126:129]
	v_mfma_f32_16x16x32_bf16 v[122:125], v[154:157], v[178:181], v[122:125]
	v_mfma_f32_16x16x32_bf16 v[118:121], v[146:149], v[186:189], v[118:121]
	v_mfma_f32_16x16x32_bf16 v[114:117], v[154:157], v[186:189], v[114:117]
	v_mfma_f32_16x16x32_bf16 v[102:105], v[146:149], v[196:199], v[102:105]
	v_mfma_f32_16x16x32_bf16 v[98:101], v[154:157], v[196:199], v[98:101]
	v_mfma_f32_16x16x32_bf16 v[86:89], v[146:149], v[204:207], v[86:89]
	v_mfma_f32_16x16x32_bf16 v[82:85], v[154:157], v[204:207], v[82:85]
	s_setprio 0
	s_setprio 1
	v_mfma_f32_16x16x32_bf16 v[110:113], v[158:161], v[174:177], v[110:113]
	v_mfma_f32_16x16x32_bf16 v[106:109], v[166:169], v[174:177], v[106:109]
	v_mfma_f32_16x16x32_bf16 v[94:97], v[158:161], v[182:185], v[94:97]
	v_mfma_f32_16x16x32_bf16 v[90:93], v[166:169], v[182:185], v[90:93]
	v_mfma_f32_16x16x32_bf16 v[78:81], v[158:161], v[192:195], v[78:81]
	v_mfma_f32_16x16x32_bf16 v[74:77], v[166:169], v[192:195], v[74:77]
	v_mfma_f32_16x16x32_bf16 v[70:73], v[158:161], v[200:203], v[70:73]
	v_mfma_f32_16x16x32_bf16 v[66:69], v[166:169], v[200:203], v[66:69]
	v_mfma_f32_16x16x32_bf16 v[110:113], v[162:165], v[178:181], v[110:113]
	v_mfma_f32_16x16x32_bf16 v[106:109], v[170:173], v[178:181], v[106:109]
	v_mfma_f32_16x16x32_bf16 v[94:97], v[162:165], v[186:189], v[94:97]
	v_mfma_f32_16x16x32_bf16 v[90:93], v[170:173], v[186:189], v[90:93]
	v_mfma_f32_16x16x32_bf16 v[78:81], v[162:165], v[196:199], v[78:81]
	v_mfma_f32_16x16x32_bf16 v[74:77], v[170:173], v[196:199], v[74:77]
	v_mfma_f32_16x16x32_bf16 v[70:73], v[162:165], v[204:207], v[70:73]
	v_mfma_f32_16x16x32_bf16 v[66:69], v[170:173], v[204:207], v[66:69]
	s_setprio 0
	s_barrier
	s_add_i32 m0, s85, s49
	s_add_u32 s100, s44, 0x80
	s_addc_u32 s101, s45, 0
	ds_read_b128 v[174:177], v141 offset:49152
	ds_read_b128 v[178:181], v141 offset:50176
	ds_read_b128 v[182:185], v141 offset:51200
	ds_read_b128 v[186:189], v141 offset:52224
	ds_read_b128 v[192:195], v141 offset:53248
	ds_read_b128 v[196:199], v141 offset:54272
	ds_read_b128 v[200:203], v141 offset:55296
	ds_read_b128 v[204:207], v141 offset:56320
	s_add_i32 m0, m0, 0x2000
	s_add_u32 s44, s44, 0x40080
	s_addc_u32 s45, s45, 0
	s_add_i32 s85, s93, s49
	s_mov_b32 m0, s85
	s_nop 0
	s_add_i32 m0, s85, 0x2000
	s_sub_u32 s100, s58, 0x3ff80
	s_subb_u32 s101, s59, 0
	s_mov_b32 m0, s71
	s_nop 0
	s_mov_b32 m0, s74
	s_nop 0
	s_waitcnt vmcnt(0)
	s_waitcnt lgkmcnt(0)
	s_barrier
	s_setprio 1
	s_waitcnt lgkmcnt(0)
	v_mfma_f32_16x16x32_bf16 v[62:65], v[142:145], v[174:177], v[62:65]
	v_mfma_f32_16x16x32_bf16 v[58:61], v[150:153], v[174:177], v[58:61]
	v_mfma_f32_16x16x32_bf16 v[54:57], v[142:145], v[182:185], v[54:57]
	v_mfma_f32_16x16x32_bf16 v[50:53], v[150:153], v[182:185], v[50:53]
	v_mfma_f32_16x16x32_bf16 v[38:41], v[142:145], v[192:195], v[38:41]
	v_mfma_f32_16x16x32_bf16 v[34:37], v[150:153], v[192:195], v[34:37]
	v_mfma_f32_16x16x32_bf16 v[22:25], v[142:145], v[200:203], v[22:25]
	v_mfma_f32_16x16x32_bf16 v[18:21], v[150:153], v[200:203], v[18:21]
	v_mfma_f32_16x16x32_bf16 v[62:65], v[146:149], v[178:181], v[62:65]
	v_mfma_f32_16x16x32_bf16 v[58:61], v[154:157], v[178:181], v[58:61]
	v_mfma_f32_16x16x32_bf16 v[54:57], v[146:149], v[186:189], v[54:57]
	v_mfma_f32_16x16x32_bf16 v[50:53], v[154:157], v[186:189], v[50:53]
	v_mfma_f32_16x16x32_bf16 v[38:41], v[146:149], v[196:199], v[38:41]
	v_mfma_f32_16x16x32_bf16 v[34:37], v[154:157], v[196:199], v[34:37]
	v_mfma_f32_16x16x32_bf16 v[22:25], v[146:149], v[204:207], v[22:25]
	v_mfma_f32_16x16x32_bf16 v[18:21], v[154:157], v[204:207], v[18:21]
	s_setprio 0
	s_setprio 1
	v_mfma_f32_16x16x32_bf16 v[46:49], v[158:161], v[174:177], v[46:49]
	v_mfma_f32_16x16x32_bf16 v[42:45], v[166:169], v[174:177], v[42:45]
	v_mfma_f32_16x16x32_bf16 v[30:33], v[158:161], v[182:185], v[30:33]
	v_mfma_f32_16x16x32_bf16 v[26:29], v[166:169], v[182:185], v[26:29]
	v_mfma_f32_16x16x32_bf16 v[14:17], v[158:161], v[192:195], v[14:17]
	v_mfma_f32_16x16x32_bf16 v[10:13], v[166:169], v[192:195], v[10:13]
	v_mfma_f32_16x16x32_bf16 v[6:9], v[158:161], v[200:203], v[6:9]
	v_mfma_f32_16x16x32_bf16 v[2:5], v[166:169], v[200:203], v[2:5]
	v_mfma_f32_16x16x32_bf16 v[46:49], v[162:165], v[178:181], v[46:49]
	v_mfma_f32_16x16x32_bf16 v[42:45], v[170:173], v[178:181], v[42:45]
	v_mfma_f32_16x16x32_bf16 v[30:33], v[162:165], v[186:189], v[30:33]
	v_mfma_f32_16x16x32_bf16 v[26:29], v[170:173], v[186:189], v[26:29]
	v_mfma_f32_16x16x32_bf16 v[14:17], v[162:165], v[196:199], v[14:17]
	v_mfma_f32_16x16x32_bf16 v[10:13], v[170:173], v[196:199], v[10:13]
	v_mfma_f32_16x16x32_bf16 v[6:9], v[162:165], v[204:207], v[6:9]
	v_mfma_f32_16x16x32_bf16 v[2:5], v[170:173], v[204:207], v[2:5]
	s_setprio 0
	s_barrier
	s_add_i32 s81, s81, 2
	s_add_u32 s38, s38, 0x100
	s_addc_u32 s39, s39, 0
	s_cmp_lt_u32 s81, 14
	s_waitcnt vmcnt(0)
	s_cmpk_gt_u32 s40, 0xff
	s_cbranch_scc1 .LBB0_163
	s_barrier
